# P1 EpiZ: non-temporal hint on the write-once f32 k/v/rope-key output stores (80 dwordx4 stores)
# baseline (speedup 1.0000x reference)
.LBB0_291:
	s_andn2_b64 vcc, exec, s[14:15]
	s_cbranch_vccnz .LBB0_293
	v_readlane_b32 s2, v245, 37
	v_readlane_b32 s3, v245, 38
	s_load_dwordx16 s[36:51], s[2:3], 0x80
	s_lshl_b32 s14, s68, 2
	v_lshlrev_b64 v[176:177], 11, v[158:159]
	v_ashrrev_i32_e32 v157, 31, v156
	v_cvt_pk_bf16_f32 v178, v126, v127
	s_waitcnt lgkmcnt(0)
	s_add_u32 s14, s50, s14
	s_addc_u32 s15, s51, 0
	v_lshl_add_u64 v[176:177], s[14:15], 0, v[176:177]
	v_lshl_add_u64 v[176:177], v[160:161], 2, v[176:177]
	global_store_dwordx4 v[176:177], v[126:129], off offset:-4096 nt
	global_store_dwordx4 v[176:177], v[122:125], off offset:-4032 nt
	v_lshlrev_b64 v[176:177], 10, v[156:157]
	v_lshl_add_u64 v[176:177], s[22:23], 0, v[176:177]
	v_lshl_add_u64 v[176:177], v[160:161], 1, v[176:177]
	v_cvt_pk_bf16_f32 v179, v128, v129
	global_store_dwordx2 v[176:177], v[178:179], off offset:-2048
	v_cvt_pk_bf16_f32 v178, v122, v123
	v_cvt_pk_bf16_f32 v179, v124, v125
	global_store_dwordx2 v[176:177], v[178:179], off offset:-2016

.LBB0_294:
	s_andn2_b64 vcc, exec, s[14:15]
	s_cbranch_vccnz .LBB0_296
	v_readlane_b32 s2, v245, 37
	v_readlane_b32 s3, v245, 38
	s_load_dwordx16 s[36:51], s[2:3], 0x80
	s_lshl_b32 s14, s61, 2
	v_lshlrev_b64 v[176:177], 11, v[158:159]
	v_ashrrev_i32_e32 v157, 31, v156
	v_cvt_pk_bf16_f32 v178, v126, v127
	s_waitcnt lgkmcnt(0)
	s_add_u32 s14, s50, s14
	s_addc_u32 s15, s51, 0
	v_lshl_add_u64 v[176:177], s[14:15], 0, v[176:177]
	v_lshl_add_u64 v[176:177], v[160:161], 2, v[176:177]
	global_store_dwordx4 v[176:177], v[126:129], off offset:-2048 nt
	global_store_dwordx4 v[176:177], v[122:125], off offset:-1984 nt
	v_lshlrev_b64 v[176:177], 10, v[156:157]
	v_lshl_add_u64 v[176:177], s[28:29], 0, v[176:177]
	v_lshl_add_u64 v[176:177], v[160:161], 1, v[176:177]
	v_cvt_pk_bf16_f32 v179, v128, v129
	global_store_dwordx2 v[176:177], v[178:179], off offset:-1024
	v_cvt_pk_bf16_f32 v178, v122, v123
	v_cvt_pk_bf16_f32 v179, v124, v125
	global_store_dwordx2 v[176:177], v[178:179], off offset:-992

.LBB0_305:
	s_andn2_b64 vcc, exec, s[84:85]
	s_cbranch_vccnz .LBB0_307
	v_readlane_b32 s2, v245, 37
	v_readlane_b32 s3, v245, 38
	s_load_dwordx16 s[80:95], s[2:3], 0x80
	s_lshl_b32 s38, s68, 2
	v_lshlrev_b64 v[126:127], 11, v[124:125]
	v_ashrrev_i32_e32 v123, 31, v122
	v_cvt_pk_bf16_f32 v128, v118, v119
	s_waitcnt lgkmcnt(0)
	s_add_u32 s38, s94, s38
	s_addc_u32 s39, s95, 0
	v_lshl_add_u64 v[126:127], s[38:39], 0, v[126:127]
	v_lshl_add_u64 v[126:127], v[160:161], 2, v[126:127]
	global_store_dwordx4 v[126:127], v[118:121], off offset:-4096 nt
	global_store_dwordx4 v[126:127], v[114:117], off offset:-4032 nt
	v_lshlrev_b64 v[126:127], 10, v[122:123]
	v_lshl_add_u64 v[126:127], s[22:23], 0, v[126:127]
	v_lshl_add_u64 v[126:127], v[160:161], 1, v[126:127]
	v_cvt_pk_bf16_f32 v129, v120, v121
	global_store_dwordx2 v[126:127], v[128:129], off offset:-2048
	v_cvt_pk_bf16_f32 v128, v114, v115
	v_cvt_pk_bf16_f32 v129, v116, v117
	global_store_dwordx2 v[126:127], v[128:129], off offset:-2016

.LBB0_308:
	s_andn2_b64 vcc, exec, s[84:85]
	s_cbranch_vccnz .LBB0_310
	v_readlane_b32 s2, v245, 37
	v_readlane_b32 s3, v245, 38
	s_load_dwordx16 s[80:95], s[2:3], 0x80
	s_lshl_b32 s38, s61, 2
	v_lshlrev_b64 v[126:127], 11, v[124:125]
	v_ashrrev_i32_e32 v123, 31, v122
	v_cvt_pk_bf16_f32 v128, v118, v119
	s_waitcnt lgkmcnt(0)
	s_add_u32 s38, s94, s38
	s_addc_u32 s39, s95, 0
	v_lshl_add_u64 v[126:127], s[38:39], 0, v[126:127]
	v_lshl_add_u64 v[126:127], v[160:161], 2, v[126:127]
	global_store_dwordx4 v[126:127], v[118:121], off offset:-2048 nt
	global_store_dwordx4 v[126:127], v[114:117], off offset:-1984 nt
	v_lshlrev_b64 v[126:127], 10, v[122:123]
	v_lshl_add_u64 v[126:127], s[28:29], 0, v[126:127]
	v_lshl_add_u64 v[126:127], v[160:161], 1, v[126:127]
	v_cvt_pk_bf16_f32 v129, v120, v121
	global_store_dwordx2 v[126:127], v[128:129], off offset:-1024
	v_cvt_pk_bf16_f32 v128, v114, v115
	v_cvt_pk_bf16_f32 v129, v116, v117
	global_store_dwordx2 v[126:127], v[128:129], off offset:-992

.LBB0_319:
	s_andn2_b64 vcc, exec, s[84:85]
	s_cbranch_vccnz .LBB0_321
	v_readlane_b32 s2, v245, 37
	v_readlane_b32 s3, v245, 38
	s_load_dwordx16 s[80:95], s[2:3], 0x80
	s_lshl_b32 s38, s68, 2
	v_lshlrev_b64 v[118:119], 11, v[116:117]
	v_ashrrev_i32_e32 v115, 31, v114
	v_cvt_pk_bf16_f32 v120, v110, v111
	s_waitcnt lgkmcnt(0)
	s_add_u32 s38, s94, s38
	s_addc_u32 s39, s95, 0
	v_lshl_add_u64 v[118:119], s[38:39], 0, v[118:119]
	v_lshl_add_u64 v[118:119], v[160:161], 2, v[118:119]
	global_store_dwordx4 v[118:119], v[110:113], off offset:-4096 nt
	global_store_dwordx4 v[118:119], v[106:109], off offset:-4032 nt
	v_lshlrev_b64 v[118:119], 10, v[114:115]
	v_lshl_add_u64 v[118:119], s[22:23], 0, v[118:119]
	v_lshl_add_u64 v[118:119], v[160:161], 1, v[118:119]
	v_cvt_pk_bf16_f32 v121, v112, v113
	global_store_dwordx2 v[118:119], v[120:121], off offset:-2048
	v_cvt_pk_bf16_f32 v120, v106, v107
	v_cvt_pk_bf16_f32 v121, v108, v109
	global_store_dwordx2 v[118:119], v[120:121], off offset:-2016

.LBB0_322:
	s_andn2_b64 vcc, exec, s[84:85]
	s_cbranch_vccnz .LBB0_324
	v_readlane_b32 s2, v245, 37
	v_readlane_b32 s3, v245, 38
	s_load_dwordx16 s[80:95], s[2:3], 0x80
	s_lshl_b32 s38, s61, 2
	v_lshlrev_b64 v[118:119], 11, v[116:117]
	v_ashrrev_i32_e32 v115, 31, v114
	v_cvt_pk_bf16_f32 v120, v110, v111
	s_waitcnt lgkmcnt(0)
	s_add_u32 s38, s94, s38
	s_addc_u32 s39, s95, 0
	v_lshl_add_u64 v[118:119], s[38:39], 0, v[118:119]
	v_lshl_add_u64 v[118:119], v[160:161], 2, v[118:119]
	global_store_dwordx4 v[118:119], v[110:113], off offset:-2048 nt
	global_store_dwordx4 v[118:119], v[106:109], off offset:-1984 nt
	v_lshlrev_b64 v[118:119], 10, v[114:115]
	v_lshl_add_u64 v[118:119], s[28:29], 0, v[118:119]
	v_lshl_add_u64 v[118:119], v[160:161], 1, v[118:119]
	v_cvt_pk_bf16_f32 v121, v112, v113
	global_store_dwordx2 v[118:119], v[120:121], off offset:-1024
	v_cvt_pk_bf16_f32 v120, v106, v107
	v_cvt_pk_bf16_f32 v121, v108, v109
	global_store_dwordx2 v[118:119], v[120:121], off offset:-992

.LBB0_333:
	s_andn2_b64 vcc, exec, s[84:85]
	s_cbranch_vccnz .LBB0_335
	v_readlane_b32 s2, v245, 37
	v_readlane_b32 s3, v245, 38
	s_load_dwordx16 s[80:95], s[2:3], 0x80
	s_lshl_b32 s38, s68, 2
	v_lshlrev_b64 v[110:111], 11, v[108:109]
	v_ashrrev_i32_e32 v107, 31, v106
	v_cvt_pk_bf16_f32 v112, v102, v103
	s_waitcnt lgkmcnt(0)
	s_add_u32 s38, s94, s38
	s_addc_u32 s39, s95, 0
	v_lshl_add_u64 v[110:111], s[38:39], 0, v[110:111]
	v_lshl_add_u64 v[110:111], v[160:161], 2, v[110:111]
	global_store_dwordx4 v[110:111], v[102:105], off offset:-4096 nt
	global_store_dwordx4 v[110:111], v[98:101], off offset:-4032 nt
	v_lshlrev_b64 v[110:111], 10, v[106:107]
	v_lshl_add_u64 v[110:111], s[22:23], 0, v[110:111]
	v_lshl_add_u64 v[110:111], v[160:161], 1, v[110:111]
	v_cvt_pk_bf16_f32 v113, v104, v105
	global_store_dwordx2 v[110:111], v[112:113], off offset:-2048
	v_cvt_pk_bf16_f32 v112, v98, v99
	v_cvt_pk_bf16_f32 v113, v100, v101
	global_store_dwordx2 v[110:111], v[112:113], off offset:-2016

.LBB0_336:
	s_andn2_b64 vcc, exec, s[84:85]
	s_cbranch_vccnz .LBB0_338
	v_readlane_b32 s2, v245, 37
	v_readlane_b32 s3, v245, 38
	s_load_dwordx16 s[80:95], s[2:3], 0x80
	s_lshl_b32 s38, s61, 2
	v_lshlrev_b64 v[110:111], 11, v[108:109]
	v_ashrrev_i32_e32 v107, 31, v106
	v_cvt_pk_bf16_f32 v112, v102, v103
	s_waitcnt lgkmcnt(0)
	s_add_u32 s38, s94, s38
	s_addc_u32 s39, s95, 0
	v_lshl_add_u64 v[110:111], s[38:39], 0, v[110:111]
	v_lshl_add_u64 v[110:111], v[160:161], 2, v[110:111]
	global_store_dwordx4 v[110:111], v[102:105], off offset:-2048 nt
	global_store_dwordx4 v[110:111], v[98:101], off offset:-1984 nt
	v_lshlrev_b64 v[110:111], 10, v[106:107]
	v_lshl_add_u64 v[110:111], s[28:29], 0, v[110:111]
	v_lshl_add_u64 v[110:111], v[160:161], 1, v[110:111]
	v_cvt_pk_bf16_f32 v113, v104, v105
	global_store_dwordx2 v[110:111], v[112:113], off offset:-1024
	v_cvt_pk_bf16_f32 v112, v98, v99
	v_cvt_pk_bf16_f32 v113, v100, v101
	global_store_dwordx2 v[110:111], v[112:113], off offset:-992

.LBB0_347:
	s_andn2_b64 vcc, exec, s[84:85]
	s_cbranch_vccnz .LBB0_349
	v_readlane_b32 s2, v245, 37
	v_readlane_b32 s3, v245, 38
	s_load_dwordx16 s[80:95], s[2:3], 0x80
	s_lshl_b32 s38, s68, 2
	v_lshlrev_b64 v[102:103], 11, v[100:101]
	v_ashrrev_i32_e32 v99, 31, v98
	v_cvt_pk_bf16_f32 v104, v94, v95
	s_waitcnt lgkmcnt(0)
	s_add_u32 s38, s94, s38
	s_addc_u32 s39, s95, 0
	v_lshl_add_u64 v[102:103], s[38:39], 0, v[102:103]
	v_lshl_add_u64 v[102:103], v[160:161], 2, v[102:103]
	global_store_dwordx4 v[102:103], v[94:97], off offset:-4096 nt
	global_store_dwordx4 v[102:103], v[90:93], off offset:-4032 nt
	v_lshlrev_b64 v[102:103], 10, v[98:99]
	v_lshl_add_u64 v[102:103], s[22:23], 0, v[102:103]
	v_lshl_add_u64 v[102:103], v[160:161], 1, v[102:103]
	v_cvt_pk_bf16_f32 v105, v96, v97
	global_store_dwordx2 v[102:103], v[104:105], off offset:-2048
	v_cvt_pk_bf16_f32 v104, v90, v91
	v_cvt_pk_bf16_f32 v105, v92, v93
	global_store_dwordx2 v[102:103], v[104:105], off offset:-2016

.LBB0_350:
	s_andn2_b64 vcc, exec, s[84:85]
	s_cbranch_vccnz .LBB0_352
	v_readlane_b32 s2, v245, 37
	v_readlane_b32 s3, v245, 38
	s_load_dwordx16 s[80:95], s[2:3], 0x80
	s_lshl_b32 s38, s61, 2
	v_lshlrev_b64 v[102:103], 11, v[100:101]
	v_ashrrev_i32_e32 v99, 31, v98
	v_cvt_pk_bf16_f32 v104, v94, v95
	s_waitcnt lgkmcnt(0)
	s_add_u32 s38, s94, s38
	s_addc_u32 s39, s95, 0
	v_lshl_add_u64 v[102:103], s[38:39], 0, v[102:103]
	v_lshl_add_u64 v[102:103], v[160:161], 2, v[102:103]
	global_store_dwordx4 v[102:103], v[94:97], off offset:-2048 nt
	global_store_dwordx4 v[102:103], v[90:93], off offset:-1984 nt
	v_lshlrev_b64 v[102:103], 10, v[98:99]
	v_lshl_add_u64 v[102:103], s[28:29], 0, v[102:103]
	v_lshl_add_u64 v[102:103], v[160:161], 1, v[102:103]
	v_cvt_pk_bf16_f32 v105, v96, v97
	global_store_dwordx2 v[102:103], v[104:105], off offset:-1024
	v_cvt_pk_bf16_f32 v104, v90, v91
	v_cvt_pk_bf16_f32 v105, v92, v93
	global_store_dwordx2 v[102:103], v[104:105], off offset:-992

.LBB0_361:
	s_andn2_b64 vcc, exec, s[84:85]
	s_cbranch_vccnz .LBB0_363
	v_readlane_b32 s2, v245, 37
	v_readlane_b32 s3, v245, 38
	s_load_dwordx16 s[80:95], s[2:3], 0x80
	s_lshl_b32 s38, s68, 2
	v_lshlrev_b64 v[94:95], 11, v[92:93]
	v_ashrrev_i32_e32 v91, 31, v90
	v_cvt_pk_bf16_f32 v96, v86, v87
	s_waitcnt lgkmcnt(0)
	s_add_u32 s38, s94, s38
	s_addc_u32 s39, s95, 0
	v_lshl_add_u64 v[94:95], s[38:39], 0, v[94:95]
	v_lshl_add_u64 v[94:95], v[160:161], 2, v[94:95]
	global_store_dwordx4 v[94:95], v[86:89], off offset:-4096 nt
	global_store_dwordx4 v[94:95], v[82:85], off offset:-4032 nt
	v_lshlrev_b64 v[94:95], 10, v[90:91]
	v_lshl_add_u64 v[94:95], s[22:23], 0, v[94:95]
	v_lshl_add_u64 v[94:95], v[160:161], 1, v[94:95]
	v_cvt_pk_bf16_f32 v97, v88, v89
	global_store_dwordx2 v[94:95], v[96:97], off offset:-2048
	v_cvt_pk_bf16_f32 v96, v82, v83
	v_cvt_pk_bf16_f32 v97, v84, v85
	global_store_dwordx2 v[94:95], v[96:97], off offset:-2016

.LBB0_364:
	s_andn2_b64 vcc, exec, s[84:85]
	s_cbranch_vccnz .LBB0_366
	v_readlane_b32 s2, v245, 37
	v_readlane_b32 s3, v245, 38
	s_load_dwordx16 s[80:95], s[2:3], 0x80
	s_lshl_b32 s38, s61, 2
	v_lshlrev_b64 v[94:95], 11, v[92:93]
	v_ashrrev_i32_e32 v91, 31, v90
	v_cvt_pk_bf16_f32 v96, v86, v87
	s_waitcnt lgkmcnt(0)
	s_add_u32 s38, s94, s38
	s_addc_u32 s39, s95, 0
	v_lshl_add_u64 v[94:95], s[38:39], 0, v[94:95]
	v_lshl_add_u64 v[94:95], v[160:161], 2, v[94:95]
	global_store_dwordx4 v[94:95], v[86:89], off offset:-2048 nt
	global_store_dwordx4 v[94:95], v[82:85], off offset:-1984 nt
	v_lshlrev_b64 v[94:95], 10, v[90:91]
	v_lshl_add_u64 v[94:95], s[28:29], 0, v[94:95]
	v_lshl_add_u64 v[94:95], v[160:161], 1, v[94:95]
	v_cvt_pk_bf16_f32 v97, v88, v89
	global_store_dwordx2 v[94:95], v[96:97], off offset:-1024
	v_cvt_pk_bf16_f32 v96, v82, v83
	v_cvt_pk_bf16_f32 v97, v84, v85
	global_store_dwordx2 v[94:95], v[96:97], off offset:-992

.LBB0_375:
	s_andn2_b64 vcc, exec, s[84:85]
	s_cbranch_vccnz .LBB0_377
	v_readlane_b32 s2, v245, 37
	v_readlane_b32 s3, v245, 38
	s_load_dwordx16 s[80:95], s[2:3], 0x80
	s_lshl_b32 s38, s68, 2
	v_lshlrev_b64 v[86:87], 11, v[84:85]
	v_ashrrev_i32_e32 v83, 31, v82
	v_cvt_pk_bf16_f32 v88, v78, v79
	s_waitcnt lgkmcnt(0)
	s_add_u32 s38, s94, s38
	s_addc_u32 s39, s95, 0
	v_lshl_add_u64 v[86:87], s[38:39], 0, v[86:87]
	v_lshl_add_u64 v[86:87], v[160:161], 2, v[86:87]
	global_store_dwordx4 v[86:87], v[78:81], off offset:-4096 nt
	global_store_dwordx4 v[86:87], v[74:77], off offset:-4032 nt
	v_lshlrev_b64 v[86:87], 10, v[82:83]
	v_lshl_add_u64 v[86:87], s[22:23], 0, v[86:87]
	v_lshl_add_u64 v[86:87], v[160:161], 1, v[86:87]
	v_cvt_pk_bf16_f32 v89, v80, v81
	global_store_dwordx2 v[86:87], v[88:89], off offset:-2048
	v_cvt_pk_bf16_f32 v88, v74, v75
	v_cvt_pk_bf16_f32 v89, v76, v77
	global_store_dwordx2 v[86:87], v[88:89], off offset:-2016

.LBB0_378:
	s_andn2_b64 vcc, exec, s[84:85]
	s_cbranch_vccnz .LBB0_380
	v_readlane_b32 s2, v245, 37
	v_readlane_b32 s3, v245, 38
	s_load_dwordx16 s[80:95], s[2:3], 0x80
	s_lshl_b32 s38, s61, 2
	v_lshlrev_b64 v[86:87], 11, v[84:85]
	v_ashrrev_i32_e32 v83, 31, v82
	v_cvt_pk_bf16_f32 v88, v78, v79
	s_waitcnt lgkmcnt(0)
	s_add_u32 s38, s94, s38
	s_addc_u32 s39, s95, 0
	v_lshl_add_u64 v[86:87], s[38:39], 0, v[86:87]
	v_lshl_add_u64 v[86:87], v[160:161], 2, v[86:87]
	global_store_dwordx4 v[86:87], v[78:81], off offset:-2048 nt
	global_store_dwordx4 v[86:87], v[74:77], off offset:-1984 nt
	v_lshlrev_b64 v[86:87], 10, v[82:83]
	v_lshl_add_u64 v[86:87], s[28:29], 0, v[86:87]
	v_lshl_add_u64 v[86:87], v[160:161], 1, v[86:87]
	v_cvt_pk_bf16_f32 v89, v80, v81
	global_store_dwordx2 v[86:87], v[88:89], off offset:-1024
	v_cvt_pk_bf16_f32 v88, v74, v75
	v_cvt_pk_bf16_f32 v89, v76, v77
	global_store_dwordx2 v[86:87], v[88:89], off offset:-992

.LBB0_389:
	s_andn2_b64 vcc, exec, s[14:15]
	s_cbranch_vccnz .LBB0_391
	v_readlane_b32 s0, v245, 37
	v_readlane_b32 s1, v245, 38
	s_load_dwordx16 s[80:95], s[0:1], 0x80
	s_lshl_b32 s14, s68, 2
	v_lshlrev_b64 v[78:79], 11, v[76:77]
	v_ashrrev_i32_e32 v75, 31, v74
	v_cvt_pk_bf16_f32 v80, v70, v71
	s_waitcnt lgkmcnt(0)
	s_mov_b64 s[48:49], s[92:93]
	s_mov_b64 s[50:51], s[94:95]
	s_add_u32 s14, s50, s14
	s_addc_u32 s15, s51, 0
	v_lshl_add_u64 v[78:79], s[14:15], 0, v[78:79]
	v_lshl_add_u64 v[78:79], v[160:161], 2, v[78:79]
	global_store_dwordx4 v[78:79], v[70:73], off offset:-4096 nt
	global_store_dwordx4 v[78:79], v[66:69], off offset:-4032 nt
	v_lshlrev_b64 v[78:79], 10, v[74:75]
	v_lshl_add_u64 v[78:79], s[22:23], 0, v[78:79]
	v_lshl_add_u64 v[78:79], v[160:161], 1, v[78:79]
	v_cvt_pk_bf16_f32 v81, v72, v73
	global_store_dwordx2 v[78:79], v[80:81], off offset:-2048
	v_cvt_pk_bf16_f32 v80, v66, v67
	v_cvt_pk_bf16_f32 v81, v68, v69
	global_store_dwordx2 v[78:79], v[80:81], off offset:-2016

.LBB0_392:
	s_andn2_b64 vcc, exec, s[14:15]
	s_cbranch_vccnz .LBB0_394
	v_readlane_b32 s0, v245, 37
	v_readlane_b32 s1, v245, 38
	s_load_dwordx16 s[80:95], s[0:1], 0x80
	s_lshl_b32 s14, s61, 2
	v_lshlrev_b64 v[78:79], 11, v[76:77]
	v_ashrrev_i32_e32 v75, 31, v74
	v_cvt_pk_bf16_f32 v80, v70, v71
	s_waitcnt lgkmcnt(0)
	s_mov_b64 s[48:49], s[92:93]
	s_mov_b64 s[50:51], s[94:95]
	s_add_u32 s14, s50, s14
	s_addc_u32 s15, s51, 0
	v_lshl_add_u64 v[78:79], s[14:15], 0, v[78:79]
	v_lshl_add_u64 v[78:79], v[160:161], 2, v[78:79]
	global_store_dwordx4 v[78:79], v[70:73], off offset:-2048 nt
	global_store_dwordx4 v[78:79], v[66:69], off offset:-1984 nt
	v_lshlrev_b64 v[78:79], 10, v[74:75]
	v_lshl_add_u64 v[78:79], s[28:29], 0, v[78:79]
	v_lshl_add_u64 v[78:79], v[160:161], 1, v[78:79]
	v_cvt_pk_bf16_f32 v81, v72, v73
	global_store_dwordx2 v[78:79], v[80:81], off offset:-1024
	v_cvt_pk_bf16_f32 v80, v66, v67
	v_cvt_pk_bf16_f32 v81, v68, v69
	global_store_dwordx2 v[78:79], v[80:81], off offset:-992

.LBB0_405:
	s_andn2_b64 vcc, exec, s[14:15]
	s_cbranch_vccnz .LBB0_407
	v_and_b32_e32 v66, 0x7cf, v156
	v_cndmask_b32_e64 v66, v168, v66, s[18:19]
	v_cvt_f32_u32_e32 v66, v66
	v_readlane_b32 s0, v245, 37
	v_readlane_b32 s1, v245, 38
	s_load_dwordx16 s[36:51], s[0:1], 0x80
	v_mul_f32_e32 v67, v164, v66
	v_mul_f32_e32 v69, 0.15915494, v67
	v_floor_f32_e32 v69, v69
	v_fmac_f32_e32 v67, 0xc0c90fdb, v69
	v_mul_f32_e32 v68, v165, v66
	v_fmac_f32_e32 v67, 0x343bbd2e, v69
	v_mul_f32_e32 v71, 0.15915494, v68
	v_mul_f32_e32 v67, 0.15915494, v67
	v_cos_f32_e32 v70, v67
	v_sin_f32_e32 v72, v67
	v_floor_f32_e32 v67, v71
	v_fmac_f32_e32 v68, 0xc0c90fdb, v67
	v_fmac_f32_e32 v68, 0x343bbd2e, v67
	v_mul_f32_e32 v67, 0.15915494, v68
	v_mul_f32_e32 v68, v166, v66
	v_mul_f32_e32 v69, 0.15915494, v68
	v_floor_f32_e32 v69, v69
	v_fmac_f32_e32 v68, 0xc0c90fdb, v69
	v_fmac_f32_e32 v68, 0x343bbd2e, v69
	v_mul_f32_e32 v68, 0.15915494, v68
	v_mul_f32_e32 v66, v167, v66
	v_cos_f32_e32 v78, v68
	v_sin_f32_e32 v80, v68
	v_mul_f32_e32 v68, 0.15915494, v66
	v_floor_f32_e32 v68, v68
	v_fmac_f32_e32 v66, 0xc0c90fdb, v68
	v_fmac_f32_e32 v66, 0x343bbd2e, v68
	v_mul_f32_e32 v66, 0.15915494, v66
	v_sin_f32_e32 v73, v67
	v_sin_f32_e32 v81, v66
	v_cos_f32_e32 v79, v66
	v_cos_f32_e32 v71, v67
	s_lshl_b32 s14, s69, 2
	v_pk_mul_f32 v[66:67], v[72:73], v[58:59]
	v_pk_mul_f32 v[68:69], v[80:81], v[60:61]
	v_pk_mul_f32 v[86:87], v[72:73], v[62:63]
	v_pk_mul_f32 v[72:73], v[80:81], v[64:65]
	s_waitcnt lgkmcnt(0)
	s_add_u32 s14, s50, s14
	v_pk_fma_f32 v[68:69], v[78:79], v[64:65], v[68:69] neg_lo:[0,0,1] neg_hi:[0,0,1]
	v_pk_fma_f32 v[72:73], v[78:79], v[60:61], v[72:73]
	s_addc_u32 s15, s51, 0
	v_lshlrev_b64 v[78:79], 7, v[158:159]
	v_lshl_add_u64 v[78:79], s[14:15], 0, v[78:79]
	v_lshlrev_b32_e32 v134, 2, v136
	v_pk_fma_f32 v[66:67], v[70:71], v[62:63], v[66:67] neg_lo:[0,0,1] neg_hi:[0,0,1]
	v_lshl_add_u64 v[78:79], v[78:79], 0, v[134:135]
	v_pk_fma_f32 v[70:71], v[70:71], v[58:59], v[86:87]
	global_store_dwordx4 v[78:79], v[66:69], off nt
	global_store_dwordx4 v[78:79], v[70:73], off offset:64 nt
	v_lshlrev_b64 v[78:79], 6, v[156:157]
	v_lshl_add_u64 v[78:79], v[138:139], 0, v[78:79]
	v_cvt_pk_bf16_f32 v66, v66, v67
	v_cvt_pk_bf16_f32 v67, v68, v69
	global_store_dwordx2 v[78:79], v[66:67], off
	v_cvt_pk_bf16_f32 v66, v70, v71
	v_cvt_pk_bf16_f32 v67, v72, v73
	global_store_dwordx2 v[78:79], v[66:67], off offset:32

.LBB0_411:
	s_andn2_b64 vcc, exec, s[14:15]
	s_cbranch_vccnz .LBB0_413
	v_readlane_b32 s0, v245, 37
	v_readlane_b32 s1, v245, 38
	s_load_dwordx16 s[36:51], s[0:1], 0x80
	s_lshl_b32 s14, s68, 2
	v_lshlrev_b64 v[66:67], 11, v[158:159]
	s_waitcnt lgkmcnt(0)
	s_add_u32 s14, s50, s14
	s_addc_u32 s15, s51, 0
	s_ashr_i32 s79, s78, 31
	v_lshl_add_u64 v[66:67], s[14:15], 0, v[66:67]
	v_lshl_add_u64 v[68:69], s[78:79], 0, v[144:145]
	v_lshl_add_u64 v[66:67], v[68:69], 2, v[66:67]
	global_store_dwordx4 v[66:67], v[62:65], off offset:512 nt
	global_store_dwordx4 v[66:67], v[58:61], off offset:576 nt
	v_lshlrev_b64 v[66:67], 10, v[156:157]
	v_lshl_add_u64 v[66:67], s[22:23], 0, v[66:67]
	v_lshl_add_u64 v[66:67], v[68:69], 1, v[66:67]
	v_cvt_pk_bf16_f32 v68, v62, v63
	v_cvt_pk_bf16_f32 v69, v64, v65
	global_store_dwordx2 v[66:67], v[68:69], off offset:256
	v_cvt_pk_bf16_f32 v68, v58, v59
	v_cvt_pk_bf16_f32 v69, v60, v61
	global_store_dwordx2 v[66:67], v[68:69], off offset:288

.LBB0_414:
	s_andn2_b64 vcc, exec, s[14:15]
	s_cbranch_vccnz .LBB0_416
	v_readlane_b32 s0, v245, 37
	v_readlane_b32 s1, v245, 38
	s_load_dwordx16 s[36:51], s[0:1], 0x80
	s_lshl_b32 s14, s61, 2
	v_lshlrev_b64 v[66:67], 11, v[158:159]
	s_waitcnt lgkmcnt(0)
	s_add_u32 s14, s50, s14
	s_addc_u32 s15, s51, 0
	s_ashr_i32 s79, s78, 31
	v_lshl_add_u64 v[66:67], s[14:15], 0, v[66:67]
	v_lshl_add_u64 v[68:69], s[78:79], 0, v[146:147]
	v_lshl_add_u64 v[66:67], v[68:69], 2, v[66:67]
	global_store_dwordx4 v[66:67], v[62:65], off offset:512 nt
	global_store_dwordx4 v[66:67], v[58:61], off offset:576 nt
	v_lshlrev_b64 v[66:67], 10, v[156:157]
	v_lshl_add_u64 v[66:67], s[28:29], 0, v[66:67]
	v_lshl_add_u64 v[66:67], v[68:69], 1, v[66:67]
	v_cvt_pk_bf16_f32 v68, v62, v63
	v_cvt_pk_bf16_f32 v69, v64, v65
	global_store_dwordx2 v[66:67], v[68:69], off offset:256
	v_cvt_pk_bf16_f32 v68, v58, v59
	v_cvt_pk_bf16_f32 v69, v60, v61
	global_store_dwordx2 v[66:67], v[68:69], off offset:288

.LBB0_441:
	s_andn2_b64 vcc, exec, s[88:89]
	s_cbranch_vccnz .LBB0_443
	v_and_b32_e32 v58, 0x7df, v122
	v_cndmask_b32_e64 v58, v169, v58, s[18:19]
	v_cvt_f32_u32_e32 v58, v58
	v_readlane_b32 s0, v245, 37
	v_readlane_b32 s1, v245, 38
	s_load_dwordx16 s[80:95], s[0:1], 0x80
	v_mul_f32_e32 v59, v164, v58
	v_mul_f32_e32 v61, 0.15915494, v59
	v_floor_f32_e32 v61, v61
	v_fmac_f32_e32 v59, 0xc0c90fdb, v61
	v_mul_f32_e32 v60, v165, v58
	v_fmac_f32_e32 v59, 0x343bbd2e, v61
	v_mul_f32_e32 v63, 0.15915494, v60
	v_mul_f32_e32 v59, 0.15915494, v59
	v_cos_f32_e32 v62, v59
	v_sin_f32_e32 v64, v59
	v_floor_f32_e32 v59, v63
	v_fmac_f32_e32 v60, 0xc0c90fdb, v59
	v_fmac_f32_e32 v60, 0x343bbd2e, v59
	v_mul_f32_e32 v59, 0.15915494, v60
	v_mul_f32_e32 v60, v166, v58
	v_mul_f32_e32 v61, 0.15915494, v60
	v_floor_f32_e32 v61, v61
	v_fmac_f32_e32 v60, 0xc0c90fdb, v61
	v_fmac_f32_e32 v60, 0x343bbd2e, v61
	v_mul_f32_e32 v60, 0.15915494, v60
	v_mul_f32_e32 v58, v167, v58
	v_cos_f32_e32 v66, v60
	v_sin_f32_e32 v68, v60
	v_mul_f32_e32 v60, 0.15915494, v58
	v_floor_f32_e32 v60, v60
	v_fmac_f32_e32 v58, 0xc0c90fdb, v60
	v_fmac_f32_e32 v58, 0x343bbd2e, v60
	v_mul_f32_e32 v58, 0.15915494, v58
	v_sin_f32_e32 v65, v59
	v_sin_f32_e32 v69, v58
	v_cos_f32_e32 v67, v58
	v_cos_f32_e32 v63, v59
	s_lshl_b32 s38, s69, 2
	v_pk_mul_f32 v[58:59], v[64:65], v[50:51]
	v_pk_mul_f32 v[60:61], v[68:69], v[52:53]
	v_pk_mul_f32 v[70:71], v[64:65], v[54:55]
	v_pk_mul_f32 v[64:65], v[68:69], v[56:57]
	s_waitcnt lgkmcnt(0)
	s_add_u32 s38, s94, s38
	v_pk_fma_f32 v[60:61], v[66:67], v[56:57], v[60:61] neg_lo:[0,0,1] neg_hi:[0,0,1]
	v_pk_fma_f32 v[64:65], v[66:67], v[52:53], v[64:65]
	s_addc_u32 s39, s95, 0
	v_lshlrev_b64 v[66:67], 7, v[124:125]
	v_lshl_add_u64 v[66:67], s[38:39], 0, v[66:67]
	v_lshlrev_b32_e32 v134, 2, v136
	v_pk_fma_f32 v[58:59], v[62:63], v[54:55], v[58:59] neg_lo:[0,0,1] neg_hi:[0,0,1]
	v_lshl_add_u64 v[66:67], v[66:67], 0, v[134:135]
	v_pk_fma_f32 v[62:63], v[62:63], v[50:51], v[70:71]
	global_store_dwordx4 v[66:67], v[58:61], off nt
	global_store_dwordx4 v[66:67], v[62:65], off offset:64 nt
	v_lshlrev_b64 v[66:67], 6, v[122:123]
	v_lshl_add_u64 v[66:67], v[138:139], 0, v[66:67]
	v_cvt_pk_bf16_f32 v58, v58, v59
	v_cvt_pk_bf16_f32 v59, v60, v61
	global_store_dwordx2 v[66:67], v[58:59], off
	v_cvt_pk_bf16_f32 v58, v62, v63
	v_cvt_pk_bf16_f32 v59, v64, v65
	global_store_dwordx2 v[66:67], v[58:59], off offset:32

.LBB0_447:
	s_andn2_b64 vcc, exec, s[88:89]
	s_cbranch_vccnz .LBB0_449
	v_readlane_b32 s0, v245, 37
	v_readlane_b32 s1, v245, 38
	s_load_dwordx16 s[80:95], s[0:1], 0x80
	s_lshl_b32 s38, s68, 2
	v_lshlrev_b64 v[58:59], 11, v[124:125]
	s_waitcnt lgkmcnt(0)
	s_add_u32 s38, s94, s38
	s_addc_u32 s39, s95, 0
	s_ashr_i32 s79, s78, 31
	v_lshl_add_u64 v[58:59], s[38:39], 0, v[58:59]
	v_lshl_add_u64 v[60:61], s[78:79], 0, v[144:145]
	v_lshl_add_u64 v[58:59], v[60:61], 2, v[58:59]
	global_store_dwordx4 v[58:59], v[54:57], off offset:512 nt
	global_store_dwordx4 v[58:59], v[50:53], off offset:576 nt
	v_lshlrev_b64 v[58:59], 10, v[122:123]
	v_lshl_add_u64 v[58:59], s[22:23], 0, v[58:59]
	v_lshl_add_u64 v[58:59], v[60:61], 1, v[58:59]
	v_cvt_pk_bf16_f32 v60, v54, v55
	v_cvt_pk_bf16_f32 v61, v56, v57
	global_store_dwordx2 v[58:59], v[60:61], off offset:256
	v_cvt_pk_bf16_f32 v60, v50, v51
	v_cvt_pk_bf16_f32 v61, v52, v53
	global_store_dwordx2 v[58:59], v[60:61], off offset:288

.LBB0_450:
	s_andn2_b64 vcc, exec, s[88:89]
	s_cbranch_vccnz .LBB0_452
	v_readlane_b32 s0, v245, 37
	v_readlane_b32 s1, v245, 38
	s_load_dwordx16 s[80:95], s[0:1], 0x80
	s_lshl_b32 s38, s61, 2
	v_lshlrev_b64 v[58:59], 11, v[124:125]
	s_waitcnt lgkmcnt(0)
	s_add_u32 s38, s94, s38
	s_addc_u32 s39, s95, 0
	s_ashr_i32 s79, s78, 31
	v_lshl_add_u64 v[58:59], s[38:39], 0, v[58:59]
	v_lshl_add_u64 v[60:61], s[78:79], 0, v[146:147]
	v_lshl_add_u64 v[58:59], v[60:61], 2, v[58:59]
	global_store_dwordx4 v[58:59], v[54:57], off offset:512 nt
	global_store_dwordx4 v[58:59], v[50:53], off offset:576 nt
	v_lshlrev_b64 v[58:59], 10, v[122:123]
	v_lshl_add_u64 v[58:59], s[28:29], 0, v[58:59]
	v_lshl_add_u64 v[58:59], v[60:61], 1, v[58:59]
	v_cvt_pk_bf16_f32 v60, v54, v55
	v_cvt_pk_bf16_f32 v61, v56, v57
	global_store_dwordx2 v[58:59], v[60:61], off offset:256
	v_cvt_pk_bf16_f32 v60, v50, v51
	v_cvt_pk_bf16_f32 v61, v52, v53
	global_store_dwordx2 v[58:59], v[60:61], off offset:288

.LBB0_461:
	s_andn2_b64 vcc, exec, s[88:89]
	s_cbranch_vccnz .LBB0_463
	v_and_b32_e32 v50, 0x7ef, v114
	v_cndmask_b32_e64 v50, v170, v50, s[18:19]
	v_cvt_f32_u32_e32 v50, v50
	v_readlane_b32 s0, v245, 37
	v_readlane_b32 s1, v245, 38
	s_load_dwordx16 s[80:95], s[0:1], 0x80
	v_mul_f32_e32 v51, v164, v50
	v_mul_f32_e32 v53, 0.15915494, v51
	v_floor_f32_e32 v53, v53
	v_fmac_f32_e32 v51, 0xc0c90fdb, v53
	v_mul_f32_e32 v52, v165, v50
	v_fmac_f32_e32 v51, 0x343bbd2e, v53
	v_mul_f32_e32 v55, 0.15915494, v52
	v_mul_f32_e32 v51, 0.15915494, v51
	v_cos_f32_e32 v54, v51
	v_sin_f32_e32 v56, v51
	v_floor_f32_e32 v51, v55
	v_fmac_f32_e32 v52, 0xc0c90fdb, v51
	v_fmac_f32_e32 v52, 0x343bbd2e, v51
	v_mul_f32_e32 v51, 0.15915494, v52
	v_mul_f32_e32 v52, v166, v50
	v_mul_f32_e32 v53, 0.15915494, v52
	v_floor_f32_e32 v53, v53
	v_fmac_f32_e32 v52, 0xc0c90fdb, v53
	v_fmac_f32_e32 v52, 0x343bbd2e, v53
	v_mul_f32_e32 v52, 0.15915494, v52
	v_mul_f32_e32 v50, v167, v50
	v_cos_f32_e32 v58, v52
	v_sin_f32_e32 v60, v52
	v_mul_f32_e32 v52, 0.15915494, v50
	v_floor_f32_e32 v52, v52
	v_fmac_f32_e32 v50, 0xc0c90fdb, v52
	v_fmac_f32_e32 v50, 0x343bbd2e, v52
	v_mul_f32_e32 v50, 0.15915494, v50
	v_sin_f32_e32 v57, v51
	v_sin_f32_e32 v61, v50
	v_cos_f32_e32 v59, v50
	v_cos_f32_e32 v55, v51
	s_lshl_b32 s38, s69, 2
	v_pk_mul_f32 v[50:51], v[56:57], v[42:43]
	v_pk_mul_f32 v[52:53], v[60:61], v[44:45]
	v_pk_mul_f32 v[62:63], v[56:57], v[46:47]
	v_pk_mul_f32 v[56:57], v[60:61], v[48:49]
	s_waitcnt lgkmcnt(0)
	s_add_u32 s38, s94, s38
	v_pk_fma_f32 v[52:53], v[58:59], v[48:49], v[52:53] neg_lo:[0,0,1] neg_hi:[0,0,1]
	v_pk_fma_f32 v[56:57], v[58:59], v[44:45], v[56:57]
	s_addc_u32 s39, s95, 0
	v_lshlrev_b64 v[58:59], 7, v[116:117]
	v_lshl_add_u64 v[58:59], s[38:39], 0, v[58:59]
	v_lshlrev_b32_e32 v134, 2, v136
	v_pk_fma_f32 v[50:51], v[54:55], v[46:47], v[50:51] neg_lo:[0,0,1] neg_hi:[0,0,1]
	v_lshl_add_u64 v[58:59], v[58:59], 0, v[134:135]
	v_pk_fma_f32 v[54:55], v[54:55], v[42:43], v[62:63]
	global_store_dwordx4 v[58:59], v[50:53], off nt
	global_store_dwordx4 v[58:59], v[54:57], off offset:64 nt
	v_lshlrev_b64 v[58:59], 6, v[114:115]
	v_lshl_add_u64 v[58:59], v[138:139], 0, v[58:59]
	v_cvt_pk_bf16_f32 v50, v50, v51
	v_cvt_pk_bf16_f32 v51, v52, v53
	global_store_dwordx2 v[58:59], v[50:51], off
	v_cvt_pk_bf16_f32 v50, v54, v55
	v_cvt_pk_bf16_f32 v51, v56, v57
	global_store_dwordx2 v[58:59], v[50:51], off offset:32

.LBB0_467:
	s_andn2_b64 vcc, exec, s[88:89]
	s_cbranch_vccnz .LBB0_469
	v_readlane_b32 s0, v245, 37
	v_readlane_b32 s1, v245, 38
	s_load_dwordx16 s[80:95], s[0:1], 0x80
	s_lshl_b32 s38, s68, 2
	v_lshlrev_b64 v[50:51], 11, v[116:117]
	s_waitcnt lgkmcnt(0)
	s_add_u32 s38, s94, s38
	s_addc_u32 s39, s95, 0
	s_ashr_i32 s79, s78, 31
	v_lshl_add_u64 v[50:51], s[38:39], 0, v[50:51]
	v_lshl_add_u64 v[52:53], s[78:79], 0, v[144:145]
	v_lshl_add_u64 v[50:51], v[52:53], 2, v[50:51]
	global_store_dwordx4 v[50:51], v[46:49], off offset:512 nt
	global_store_dwordx4 v[50:51], v[42:45], off offset:576 nt
	v_lshlrev_b64 v[50:51], 10, v[114:115]
	v_lshl_add_u64 v[50:51], s[22:23], 0, v[50:51]
	v_lshl_add_u64 v[50:51], v[52:53], 1, v[50:51]
	v_cvt_pk_bf16_f32 v52, v46, v47
	v_cvt_pk_bf16_f32 v53, v48, v49
	global_store_dwordx2 v[50:51], v[52:53], off offset:256
	v_cvt_pk_bf16_f32 v52, v42, v43
	v_cvt_pk_bf16_f32 v53, v44, v45
	global_store_dwordx2 v[50:51], v[52:53], off offset:288

.LBB0_470:
	s_andn2_b64 vcc, exec, s[88:89]
	s_cbranch_vccnz .LBB0_472
	v_readlane_b32 s0, v245, 37
	v_readlane_b32 s1, v245, 38
	s_load_dwordx16 s[80:95], s[0:1], 0x80
	s_lshl_b32 s38, s61, 2
	v_lshlrev_b64 v[50:51], 11, v[116:117]
	s_waitcnt lgkmcnt(0)
	s_add_u32 s38, s94, s38
	s_addc_u32 s39, s95, 0
	s_ashr_i32 s79, s78, 31
	v_lshl_add_u64 v[50:51], s[38:39], 0, v[50:51]
	v_lshl_add_u64 v[52:53], s[78:79], 0, v[146:147]
	v_lshl_add_u64 v[50:51], v[52:53], 2, v[50:51]
	global_store_dwordx4 v[50:51], v[46:49], off offset:512 nt
	global_store_dwordx4 v[50:51], v[42:45], off offset:576 nt
	v_lshlrev_b64 v[50:51], 10, v[114:115]
	v_lshl_add_u64 v[50:51], s[28:29], 0, v[50:51]
	v_lshl_add_u64 v[50:51], v[52:53], 1, v[50:51]
	v_cvt_pk_bf16_f32 v52, v46, v47
	v_cvt_pk_bf16_f32 v53, v48, v49
	global_store_dwordx2 v[50:51], v[52:53], off offset:256
	v_cvt_pk_bf16_f32 v52, v42, v43
	v_cvt_pk_bf16_f32 v53, v44, v45
	global_store_dwordx2 v[50:51], v[52:53], off offset:288

.LBB0_481:
	s_andn2_b64 vcc, exec, s[88:89]
	s_cbranch_vccnz .LBB0_483
	v_and_b32_e32 v42, 0x7ff, v106
	v_cndmask_b32_e64 v42, v171, v42, s[18:19]
	v_cvt_f32_u32_e32 v42, v42
	v_readlane_b32 s0, v245, 37
	v_readlane_b32 s1, v245, 38
	s_load_dwordx16 s[80:95], s[0:1], 0x80
	v_mul_f32_e32 v43, v164, v42
	v_mul_f32_e32 v45, 0.15915494, v43
	v_floor_f32_e32 v45, v45
	v_fmac_f32_e32 v43, 0xc0c90fdb, v45
	v_mul_f32_e32 v44, v165, v42
	v_fmac_f32_e32 v43, 0x343bbd2e, v45
	v_mul_f32_e32 v47, 0.15915494, v44
	v_mul_f32_e32 v43, 0.15915494, v43
	v_cos_f32_e32 v46, v43
	v_sin_f32_e32 v48, v43
	v_floor_f32_e32 v43, v47
	v_fmac_f32_e32 v44, 0xc0c90fdb, v43
	v_fmac_f32_e32 v44, 0x343bbd2e, v43
	v_mul_f32_e32 v43, 0.15915494, v44
	v_mul_f32_e32 v44, v166, v42
	v_mul_f32_e32 v45, 0.15915494, v44
	v_floor_f32_e32 v45, v45
	v_fmac_f32_e32 v44, 0xc0c90fdb, v45
	v_fmac_f32_e32 v44, 0x343bbd2e, v45
	v_mul_f32_e32 v44, 0.15915494, v44
	v_mul_f32_e32 v42, v167, v42
	v_cos_f32_e32 v50, v44
	v_sin_f32_e32 v52, v44
	v_mul_f32_e32 v44, 0.15915494, v42
	v_floor_f32_e32 v44, v44
	v_fmac_f32_e32 v42, 0xc0c90fdb, v44
	v_fmac_f32_e32 v42, 0x343bbd2e, v44
	v_mul_f32_e32 v42, 0.15915494, v42
	v_sin_f32_e32 v49, v43
	v_sin_f32_e32 v53, v42
	v_cos_f32_e32 v51, v42
	v_cos_f32_e32 v47, v43
	s_lshl_b32 s38, s69, 2
	v_pk_mul_f32 v[42:43], v[48:49], v[34:35]
	v_pk_mul_f32 v[44:45], v[52:53], v[36:37]
	v_pk_mul_f32 v[54:55], v[48:49], v[38:39]
	v_pk_mul_f32 v[48:49], v[52:53], v[40:41]
	s_waitcnt lgkmcnt(0)
	s_add_u32 s38, s94, s38
	v_pk_fma_f32 v[44:45], v[50:51], v[40:41], v[44:45] neg_lo:[0,0,1] neg_hi:[0,0,1]
	v_pk_fma_f32 v[48:49], v[50:51], v[36:37], v[48:49]
	s_addc_u32 s39, s95, 0
	v_lshlrev_b64 v[50:51], 7, v[108:109]
	v_lshl_add_u64 v[50:51], s[38:39], 0, v[50:51]
	v_lshlrev_b32_e32 v134, 2, v136
	v_pk_fma_f32 v[42:43], v[46:47], v[38:39], v[42:43] neg_lo:[0,0,1] neg_hi:[0,0,1]
	v_lshl_add_u64 v[50:51], v[50:51], 0, v[134:135]
	v_pk_fma_f32 v[46:47], v[46:47], v[34:35], v[54:55]
	global_store_dwordx4 v[50:51], v[42:45], off nt
	global_store_dwordx4 v[50:51], v[46:49], off offset:64 nt
	v_lshlrev_b64 v[50:51], 6, v[106:107]
	v_lshl_add_u64 v[50:51], v[138:139], 0, v[50:51]
	v_cvt_pk_bf16_f32 v42, v42, v43
	v_cvt_pk_bf16_f32 v43, v44, v45
	global_store_dwordx2 v[50:51], v[42:43], off
	v_cvt_pk_bf16_f32 v42, v46, v47
	v_cvt_pk_bf16_f32 v43, v48, v49
	global_store_dwordx2 v[50:51], v[42:43], off offset:32

.LBB0_487:
	s_andn2_b64 vcc, exec, s[88:89]
	s_cbranch_vccnz .LBB0_489
	v_readlane_b32 s0, v245, 37
	v_readlane_b32 s1, v245, 38
	s_load_dwordx16 s[80:95], s[0:1], 0x80
	s_lshl_b32 s38, s68, 2
	v_lshlrev_b64 v[42:43], 11, v[108:109]
	s_waitcnt lgkmcnt(0)
	s_add_u32 s38, s94, s38
	s_addc_u32 s39, s95, 0
	s_ashr_i32 s79, s78, 31
	v_lshl_add_u64 v[42:43], s[38:39], 0, v[42:43]
	v_lshl_add_u64 v[44:45], s[78:79], 0, v[144:145]
	v_lshl_add_u64 v[42:43], v[44:45], 2, v[42:43]
	global_store_dwordx4 v[42:43], v[38:41], off offset:512 nt
	global_store_dwordx4 v[42:43], v[34:37], off offset:576 nt
	v_lshlrev_b64 v[42:43], 10, v[106:107]
	v_lshl_add_u64 v[42:43], s[22:23], 0, v[42:43]
	v_lshl_add_u64 v[42:43], v[44:45], 1, v[42:43]
	v_cvt_pk_bf16_f32 v44, v38, v39
	v_cvt_pk_bf16_f32 v45, v40, v41
	global_store_dwordx2 v[42:43], v[44:45], off offset:256
	v_cvt_pk_bf16_f32 v44, v34, v35
	v_cvt_pk_bf16_f32 v45, v36, v37
	global_store_dwordx2 v[42:43], v[44:45], off offset:288

.LBB0_490:
	s_andn2_b64 vcc, exec, s[88:89]
	s_cbranch_vccnz .LBB0_492
	v_readlane_b32 s0, v245, 37
	v_readlane_b32 s1, v245, 38
	s_load_dwordx16 s[80:95], s[0:1], 0x80
	s_lshl_b32 s38, s61, 2
	v_lshlrev_b64 v[42:43], 11, v[108:109]
	s_waitcnt lgkmcnt(0)
	s_add_u32 s38, s94, s38
	s_addc_u32 s39, s95, 0
	s_ashr_i32 s79, s78, 31
	v_lshl_add_u64 v[42:43], s[38:39], 0, v[42:43]
	v_lshl_add_u64 v[44:45], s[78:79], 0, v[146:147]
	v_lshl_add_u64 v[42:43], v[44:45], 2, v[42:43]
	global_store_dwordx4 v[42:43], v[38:41], off offset:512 nt
	global_store_dwordx4 v[42:43], v[34:37], off offset:576 nt
	v_lshlrev_b64 v[42:43], 10, v[106:107]
	v_lshl_add_u64 v[42:43], s[28:29], 0, v[42:43]
	v_lshl_add_u64 v[42:43], v[44:45], 1, v[42:43]
	v_cvt_pk_bf16_f32 v44, v38, v39
	v_cvt_pk_bf16_f32 v45, v40, v41
	global_store_dwordx2 v[42:43], v[44:45], off offset:256
	v_cvt_pk_bf16_f32 v44, v34, v35
	v_cvt_pk_bf16_f32 v45, v36, v37
	global_store_dwordx2 v[42:43], v[44:45], off offset:288

.LBB0_501:
	s_andn2_b64 vcc, exec, s[88:89]
	s_cbranch_vccnz .LBB0_503
	v_and_b32_e32 v34, 0x7cf, v98
	v_cndmask_b32_e64 v34, v168, v34, s[18:19]
	v_cvt_f32_u32_e32 v34, v34
	v_readlane_b32 s0, v245, 37
	v_readlane_b32 s1, v245, 38
	s_load_dwordx16 s[80:95], s[0:1], 0x80
	v_mul_f32_e32 v35, v164, v34
	v_mul_f32_e32 v37, 0.15915494, v35
	v_floor_f32_e32 v37, v37
	v_fmac_f32_e32 v35, 0xc0c90fdb, v37
	v_mul_f32_e32 v36, v165, v34
	v_fmac_f32_e32 v35, 0x343bbd2e, v37
	v_mul_f32_e32 v39, 0.15915494, v36
	v_mul_f32_e32 v35, 0.15915494, v35
	v_cos_f32_e32 v38, v35
	v_sin_f32_e32 v40, v35
	v_floor_f32_e32 v35, v39
	v_fmac_f32_e32 v36, 0xc0c90fdb, v35
	v_fmac_f32_e32 v36, 0x343bbd2e, v35
	v_mul_f32_e32 v35, 0.15915494, v36
	v_mul_f32_e32 v36, v166, v34
	v_mul_f32_e32 v37, 0.15915494, v36
	v_floor_f32_e32 v37, v37
	v_fmac_f32_e32 v36, 0xc0c90fdb, v37
	v_fmac_f32_e32 v36, 0x343bbd2e, v37
	v_mul_f32_e32 v36, 0.15915494, v36
	v_mul_f32_e32 v34, v167, v34
	v_cos_f32_e32 v42, v36
	v_sin_f32_e32 v44, v36
	v_mul_f32_e32 v36, 0.15915494, v34
	v_floor_f32_e32 v36, v36
	v_fmac_f32_e32 v34, 0xc0c90fdb, v36
	v_fmac_f32_e32 v34, 0x343bbd2e, v36
	v_mul_f32_e32 v34, 0.15915494, v34
	v_sin_f32_e32 v41, v35
	v_sin_f32_e32 v45, v34
	v_cos_f32_e32 v43, v34
	v_cos_f32_e32 v39, v35
	s_lshl_b32 s38, s69, 2
	v_pk_mul_f32 v[34:35], v[40:41], v[26:27]
	v_pk_mul_f32 v[36:37], v[44:45], v[28:29]
	v_pk_mul_f32 v[46:47], v[40:41], v[30:31]
	v_pk_mul_f32 v[40:41], v[44:45], v[32:33]
	s_waitcnt lgkmcnt(0)
	s_add_u32 s38, s94, s38
	v_pk_fma_f32 v[36:37], v[42:43], v[32:33], v[36:37] neg_lo:[0,0,1] neg_hi:[0,0,1]
	v_pk_fma_f32 v[40:41], v[42:43], v[28:29], v[40:41]
	s_addc_u32 s39, s95, 0
	v_lshlrev_b64 v[42:43], 7, v[100:101]
	v_lshl_add_u64 v[42:43], s[38:39], 0, v[42:43]
	v_lshlrev_b32_e32 v134, 2, v136
	v_pk_fma_f32 v[34:35], v[38:39], v[30:31], v[34:35] neg_lo:[0,0,1] neg_hi:[0,0,1]
	v_lshl_add_u64 v[42:43], v[42:43], 0, v[134:135]
	v_pk_fma_f32 v[38:39], v[38:39], v[26:27], v[46:47]
	global_store_dwordx4 v[42:43], v[34:37], off nt
	global_store_dwordx4 v[42:43], v[38:41], off offset:64 nt
	v_lshlrev_b64 v[42:43], 6, v[98:99]
	v_lshl_add_u64 v[42:43], v[138:139], 0, v[42:43]
	v_cvt_pk_bf16_f32 v34, v34, v35
	v_cvt_pk_bf16_f32 v35, v36, v37
	global_store_dwordx2 v[42:43], v[34:35], off
	v_cvt_pk_bf16_f32 v34, v38, v39
	v_cvt_pk_bf16_f32 v35, v40, v41
	global_store_dwordx2 v[42:43], v[34:35], off offset:32

.LBB0_507:
	s_andn2_b64 vcc, exec, s[88:89]
	s_cbranch_vccnz .LBB0_509
	v_readlane_b32 s0, v245, 37
	v_readlane_b32 s1, v245, 38
	s_load_dwordx16 s[80:95], s[0:1], 0x80
	s_lshl_b32 s38, s68, 2
	v_lshlrev_b64 v[34:35], 11, v[100:101]
	s_waitcnt lgkmcnt(0)
	s_add_u32 s38, s94, s38
	s_addc_u32 s39, s95, 0
	s_ashr_i32 s79, s78, 31
	v_lshl_add_u64 v[34:35], s[38:39], 0, v[34:35]
	v_lshl_add_u64 v[36:37], s[78:79], 0, v[144:145]
	v_lshl_add_u64 v[34:35], v[36:37], 2, v[34:35]
	global_store_dwordx4 v[34:35], v[30:33], off offset:512 nt
	global_store_dwordx4 v[34:35], v[26:29], off offset:576 nt
	v_lshlrev_b64 v[34:35], 10, v[98:99]
	v_lshl_add_u64 v[34:35], s[22:23], 0, v[34:35]
	v_lshl_add_u64 v[34:35], v[36:37], 1, v[34:35]
	v_cvt_pk_bf16_f32 v36, v30, v31
	v_cvt_pk_bf16_f32 v37, v32, v33
	global_store_dwordx2 v[34:35], v[36:37], off offset:256
	v_cvt_pk_bf16_f32 v36, v26, v27
	v_cvt_pk_bf16_f32 v37, v28, v29
	global_store_dwordx2 v[34:35], v[36:37], off offset:288

.LBB0_510:
	s_andn2_b64 vcc, exec, s[88:89]
	s_cbranch_vccnz .LBB0_512
	v_readlane_b32 s0, v245, 37
	v_readlane_b32 s1, v245, 38
	s_load_dwordx16 s[80:95], s[0:1], 0x80
	s_lshl_b32 s38, s61, 2
	v_lshlrev_b64 v[34:35], 11, v[100:101]
	s_waitcnt lgkmcnt(0)
	s_add_u32 s38, s94, s38
	s_addc_u32 s39, s95, 0
	s_ashr_i32 s79, s78, 31
	v_lshl_add_u64 v[34:35], s[38:39], 0, v[34:35]
	v_lshl_add_u64 v[36:37], s[78:79], 0, v[146:147]
	v_lshl_add_u64 v[34:35], v[36:37], 2, v[34:35]
	global_store_dwordx4 v[34:35], v[30:33], off offset:512 nt
	global_store_dwordx4 v[34:35], v[26:29], off offset:576 nt
	v_lshlrev_b64 v[34:35], 10, v[98:99]
	v_lshl_add_u64 v[34:35], s[28:29], 0, v[34:35]
	v_lshl_add_u64 v[34:35], v[36:37], 1, v[34:35]
	v_cvt_pk_bf16_f32 v36, v30, v31
	v_cvt_pk_bf16_f32 v37, v32, v33
	global_store_dwordx2 v[34:35], v[36:37], off offset:256
	v_cvt_pk_bf16_f32 v36, v26, v27
	v_cvt_pk_bf16_f32 v37, v28, v29
	global_store_dwordx2 v[34:35], v[36:37], off offset:288

.LBB0_521:
	s_andn2_b64 vcc, exec, s[88:89]
	s_cbranch_vccnz .LBB0_523
	v_and_b32_e32 v26, 0x7df, v90
	v_cndmask_b32_e64 v26, v169, v26, s[18:19]
	v_cvt_f32_u32_e32 v26, v26
	v_readlane_b32 s0, v245, 37
	v_readlane_b32 s1, v245, 38
	s_load_dwordx16 s[80:95], s[0:1], 0x80
	v_mul_f32_e32 v27, v164, v26
	v_mul_f32_e32 v29, 0.15915494, v27
	v_floor_f32_e32 v29, v29
	v_fmac_f32_e32 v27, 0xc0c90fdb, v29
	v_mul_f32_e32 v28, v165, v26
	v_fmac_f32_e32 v27, 0x343bbd2e, v29
	v_mul_f32_e32 v31, 0.15915494, v28
	v_mul_f32_e32 v27, 0.15915494, v27
	v_cos_f32_e32 v30, v27
	v_sin_f32_e32 v32, v27
	v_floor_f32_e32 v27, v31
	v_fmac_f32_e32 v28, 0xc0c90fdb, v27
	v_fmac_f32_e32 v28, 0x343bbd2e, v27
	v_mul_f32_e32 v27, 0.15915494, v28
	v_mul_f32_e32 v28, v166, v26
	v_mul_f32_e32 v29, 0.15915494, v28
	v_floor_f32_e32 v29, v29
	v_fmac_f32_e32 v28, 0xc0c90fdb, v29
	v_fmac_f32_e32 v28, 0x343bbd2e, v29
	v_mul_f32_e32 v28, 0.15915494, v28
	v_mul_f32_e32 v26, v167, v26
	v_cos_f32_e32 v34, v28
	v_sin_f32_e32 v36, v28
	v_mul_f32_e32 v28, 0.15915494, v26
	v_floor_f32_e32 v28, v28
	v_fmac_f32_e32 v26, 0xc0c90fdb, v28
	v_fmac_f32_e32 v26, 0x343bbd2e, v28
	v_mul_f32_e32 v26, 0.15915494, v26
	v_sin_f32_e32 v33, v27
	v_sin_f32_e32 v37, v26
	v_cos_f32_e32 v35, v26
	v_cos_f32_e32 v31, v27
	s_lshl_b32 s38, s69, 2
	v_pk_mul_f32 v[26:27], v[32:33], v[18:19]
	v_pk_mul_f32 v[28:29], v[36:37], v[20:21]
	v_pk_mul_f32 v[38:39], v[32:33], v[22:23]
	v_pk_mul_f32 v[32:33], v[36:37], v[24:25]
	s_waitcnt lgkmcnt(0)
	s_add_u32 s38, s94, s38
	v_pk_fma_f32 v[28:29], v[34:35], v[24:25], v[28:29] neg_lo:[0,0,1] neg_hi:[0,0,1]
	v_pk_fma_f32 v[32:33], v[34:35], v[20:21], v[32:33]
	s_addc_u32 s39, s95, 0
	v_lshlrev_b64 v[34:35], 7, v[92:93]
	v_lshl_add_u64 v[34:35], s[38:39], 0, v[34:35]
	v_lshlrev_b32_e32 v134, 2, v136
	v_pk_fma_f32 v[26:27], v[30:31], v[22:23], v[26:27] neg_lo:[0,0,1] neg_hi:[0,0,1]
	v_lshl_add_u64 v[34:35], v[34:35], 0, v[134:135]
	v_pk_fma_f32 v[30:31], v[30:31], v[18:19], v[38:39]
	global_store_dwordx4 v[34:35], v[26:29], off nt
	global_store_dwordx4 v[34:35], v[30:33], off offset:64 nt
	v_lshlrev_b64 v[34:35], 6, v[90:91]
	v_lshl_add_u64 v[34:35], v[138:139], 0, v[34:35]
	v_cvt_pk_bf16_f32 v26, v26, v27
	v_cvt_pk_bf16_f32 v27, v28, v29
	global_store_dwordx2 v[34:35], v[26:27], off
	v_cvt_pk_bf16_f32 v26, v30, v31
	v_cvt_pk_bf16_f32 v27, v32, v33
	global_store_dwordx2 v[34:35], v[26:27], off offset:32

.LBB0_527:
	s_andn2_b64 vcc, exec, s[88:89]
	s_cbranch_vccnz .LBB0_529
	v_readlane_b32 s0, v245, 37
	v_readlane_b32 s1, v245, 38
	s_load_dwordx16 s[80:95], s[0:1], 0x80
	s_lshl_b32 s38, s68, 2
	v_lshlrev_b64 v[26:27], 11, v[92:93]
	s_waitcnt lgkmcnt(0)
	s_add_u32 s38, s94, s38
	s_addc_u32 s39, s95, 0
	s_ashr_i32 s79, s78, 31
	v_lshl_add_u64 v[26:27], s[38:39], 0, v[26:27]
	v_lshl_add_u64 v[28:29], s[78:79], 0, v[144:145]
	v_lshl_add_u64 v[26:27], v[28:29], 2, v[26:27]
	global_store_dwordx4 v[26:27], v[22:25], off offset:512 nt
	global_store_dwordx4 v[26:27], v[18:21], off offset:576 nt
	v_lshlrev_b64 v[26:27], 10, v[90:91]
	v_lshl_add_u64 v[26:27], s[22:23], 0, v[26:27]
	v_lshl_add_u64 v[26:27], v[28:29], 1, v[26:27]
	v_cvt_pk_bf16_f32 v28, v22, v23
	v_cvt_pk_bf16_f32 v29, v24, v25
	global_store_dwordx2 v[26:27], v[28:29], off offset:256
	v_cvt_pk_bf16_f32 v28, v18, v19
	v_cvt_pk_bf16_f32 v29, v20, v21
	global_store_dwordx2 v[26:27], v[28:29], off offset:288

.LBB0_530:
	s_andn2_b64 vcc, exec, s[88:89]
	s_cbranch_vccnz .LBB0_532
	v_readlane_b32 s0, v245, 37
	v_readlane_b32 s1, v245, 38
	s_load_dwordx16 s[80:95], s[0:1], 0x80
	s_lshl_b32 s38, s61, 2
	v_lshlrev_b64 v[26:27], 11, v[92:93]
	s_waitcnt lgkmcnt(0)
	s_add_u32 s38, s94, s38
	s_addc_u32 s39, s95, 0
	s_ashr_i32 s79, s78, 31
	v_lshl_add_u64 v[26:27], s[38:39], 0, v[26:27]
	v_lshl_add_u64 v[28:29], s[78:79], 0, v[146:147]
	v_lshl_add_u64 v[26:27], v[28:29], 2, v[26:27]
	global_store_dwordx4 v[26:27], v[22:25], off offset:512 nt
	global_store_dwordx4 v[26:27], v[18:21], off offset:576 nt
	v_lshlrev_b64 v[26:27], 10, v[90:91]
	v_lshl_add_u64 v[26:27], s[28:29], 0, v[26:27]
	v_lshl_add_u64 v[26:27], v[28:29], 1, v[26:27]
	v_cvt_pk_bf16_f32 v28, v22, v23
	v_cvt_pk_bf16_f32 v29, v24, v25
	global_store_dwordx2 v[26:27], v[28:29], off offset:256
	v_cvt_pk_bf16_f32 v28, v18, v19
	v_cvt_pk_bf16_f32 v29, v20, v21
	global_store_dwordx2 v[26:27], v[28:29], off offset:288

.LBB0_541:
	s_andn2_b64 vcc, exec, s[88:89]
	s_cbranch_vccnz .LBB0_543
	v_and_b32_e32 v18, 0x7ef, v82
	v_cndmask_b32_e64 v18, v170, v18, s[18:19]
	v_cvt_f32_u32_e32 v18, v18
	v_readlane_b32 s0, v245, 37
	v_readlane_b32 s1, v245, 38
	s_load_dwordx16 s[80:95], s[0:1], 0x80
	v_mul_f32_e32 v19, v164, v18
	v_mul_f32_e32 v21, 0.15915494, v19
	v_floor_f32_e32 v21, v21
	v_fmac_f32_e32 v19, 0xc0c90fdb, v21
	v_mul_f32_e32 v20, v165, v18
	v_fmac_f32_e32 v19, 0x343bbd2e, v21
	v_mul_f32_e32 v23, 0.15915494, v20
	v_mul_f32_e32 v19, 0.15915494, v19
	v_cos_f32_e32 v22, v19
	v_sin_f32_e32 v24, v19
	v_floor_f32_e32 v19, v23
	v_fmac_f32_e32 v20, 0xc0c90fdb, v19
	v_fmac_f32_e32 v20, 0x343bbd2e, v19
	v_mul_f32_e32 v19, 0.15915494, v20
	v_mul_f32_e32 v20, v166, v18
	v_mul_f32_e32 v21, 0.15915494, v20
	v_floor_f32_e32 v21, v21
	v_fmac_f32_e32 v20, 0xc0c90fdb, v21
	v_fmac_f32_e32 v20, 0x343bbd2e, v21
	v_mul_f32_e32 v20, 0.15915494, v20
	v_mul_f32_e32 v18, v167, v18
	v_cos_f32_e32 v26, v20
	v_sin_f32_e32 v28, v20
	v_mul_f32_e32 v20, 0.15915494, v18
	v_floor_f32_e32 v20, v20
	v_fmac_f32_e32 v18, 0xc0c90fdb, v20
	v_fmac_f32_e32 v18, 0x343bbd2e, v20
	v_mul_f32_e32 v18, 0.15915494, v18
	v_sin_f32_e32 v25, v19
	v_sin_f32_e32 v29, v18
	v_cos_f32_e32 v27, v18
	v_cos_f32_e32 v23, v19
	s_lshl_b32 s38, s69, 2
	v_pk_mul_f32 v[18:19], v[24:25], v[10:11]
	v_pk_mul_f32 v[20:21], v[28:29], v[12:13]
	v_pk_mul_f32 v[30:31], v[24:25], v[14:15]
	v_pk_mul_f32 v[24:25], v[28:29], v[16:17]
	s_waitcnt lgkmcnt(0)
	s_add_u32 s38, s94, s38
	v_pk_fma_f32 v[20:21], v[26:27], v[16:17], v[20:21] neg_lo:[0,0,1] neg_hi:[0,0,1]
	v_pk_fma_f32 v[24:25], v[26:27], v[12:13], v[24:25]
	s_addc_u32 s39, s95, 0
	v_lshlrev_b64 v[26:27], 7, v[84:85]
	v_lshl_add_u64 v[26:27], s[38:39], 0, v[26:27]
	v_lshlrev_b32_e32 v134, 2, v136
	v_pk_fma_f32 v[18:19], v[22:23], v[14:15], v[18:19] neg_lo:[0,0,1] neg_hi:[0,0,1]
	v_lshl_add_u64 v[26:27], v[26:27], 0, v[134:135]
	v_pk_fma_f32 v[22:23], v[22:23], v[10:11], v[30:31]
	global_store_dwordx4 v[26:27], v[18:21], off nt
	global_store_dwordx4 v[26:27], v[22:25], off offset:64 nt
	v_lshlrev_b64 v[26:27], 6, v[82:83]
	v_lshl_add_u64 v[26:27], v[138:139], 0, v[26:27]
	v_cvt_pk_bf16_f32 v18, v18, v19
	v_cvt_pk_bf16_f32 v19, v20, v21
	global_store_dwordx2 v[26:27], v[18:19], off
	v_cvt_pk_bf16_f32 v18, v22, v23
	v_cvt_pk_bf16_f32 v19, v24, v25
	global_store_dwordx2 v[26:27], v[18:19], off offset:32

.LBB0_547:
	s_andn2_b64 vcc, exec, s[88:89]
	s_cbranch_vccnz .LBB0_549
	v_readlane_b32 s0, v245, 37
	v_readlane_b32 s1, v245, 38
	s_load_dwordx16 s[80:95], s[0:1], 0x80
	s_lshl_b32 s38, s68, 2
	v_lshlrev_b64 v[18:19], 11, v[84:85]
	s_waitcnt lgkmcnt(0)
	s_add_u32 s38, s94, s38
	s_addc_u32 s39, s95, 0
	s_ashr_i32 s79, s78, 31
	v_lshl_add_u64 v[18:19], s[38:39], 0, v[18:19]
	v_lshl_add_u64 v[20:21], s[78:79], 0, v[144:145]
	v_lshl_add_u64 v[18:19], v[20:21], 2, v[18:19]
	global_store_dwordx4 v[18:19], v[14:17], off offset:512 nt
	global_store_dwordx4 v[18:19], v[10:13], off offset:576 nt
	v_lshlrev_b64 v[18:19], 10, v[82:83]
	v_lshl_add_u64 v[18:19], s[22:23], 0, v[18:19]
	v_lshl_add_u64 v[18:19], v[20:21], 1, v[18:19]
	v_cvt_pk_bf16_f32 v20, v14, v15
	v_cvt_pk_bf16_f32 v21, v16, v17
	global_store_dwordx2 v[18:19], v[20:21], off offset:256
	v_cvt_pk_bf16_f32 v20, v10, v11
	v_cvt_pk_bf16_f32 v21, v12, v13
	global_store_dwordx2 v[18:19], v[20:21], off offset:288

.LBB0_550:
	s_andn2_b64 vcc, exec, s[88:89]
	s_cbranch_vccnz .LBB0_552
	v_readlane_b32 s0, v245, 37
	v_readlane_b32 s1, v245, 38
	s_load_dwordx16 s[80:95], s[0:1], 0x80
	s_lshl_b32 s38, s61, 2
	v_lshlrev_b64 v[18:19], 11, v[84:85]
	s_waitcnt lgkmcnt(0)
	s_add_u32 s38, s94, s38
	s_addc_u32 s39, s95, 0
	s_ashr_i32 s79, s78, 31
	v_lshl_add_u64 v[18:19], s[38:39], 0, v[18:19]
	v_lshl_add_u64 v[20:21], s[78:79], 0, v[146:147]
	v_lshl_add_u64 v[18:19], v[20:21], 2, v[18:19]
	global_store_dwordx4 v[18:19], v[14:17], off offset:512 nt
	global_store_dwordx4 v[18:19], v[10:13], off offset:576 nt
	v_lshlrev_b64 v[18:19], 10, v[82:83]
	v_lshl_add_u64 v[18:19], s[28:29], 0, v[18:19]
	v_lshl_add_u64 v[18:19], v[20:21], 1, v[18:19]
	v_cvt_pk_bf16_f32 v20, v14, v15
	v_cvt_pk_bf16_f32 v21, v16, v17
	global_store_dwordx2 v[18:19], v[20:21], off offset:256
	v_cvt_pk_bf16_f32 v20, v10, v11
	v_cvt_pk_bf16_f32 v21, v12, v13
	global_store_dwordx2 v[18:19], v[20:21], off offset:288

.LBB0_561:
	s_andn2_b64 vcc, exec, s[12:13]
	s_cbranch_vccnz .LBB0_563
	v_and_b32_e32 v10, 0x7ff, v74
	v_cndmask_b32_e64 v10, v171, v10, s[18:19]
	v_cvt_f32_u32_e32 v10, v10
	v_readlane_b32 s0, v245, 37
	v_readlane_b32 s1, v245, 38
	s_load_dwordx16 s[36:51], s[0:1], 0x80
	v_mul_f32_e32 v11, v164, v10
	v_mul_f32_e32 v13, 0.15915494, v11
	v_floor_f32_e32 v13, v13
	v_fmac_f32_e32 v11, 0xc0c90fdb, v13
	v_mul_f32_e32 v12, v165, v10
	v_fmac_f32_e32 v11, 0x343bbd2e, v13
	v_mul_f32_e32 v15, 0.15915494, v12
	v_mul_f32_e32 v11, 0.15915494, v11
	v_cos_f32_e32 v14, v11
	v_sin_f32_e32 v16, v11
	v_floor_f32_e32 v11, v15
	v_fmac_f32_e32 v12, 0xc0c90fdb, v11
	v_fmac_f32_e32 v12, 0x343bbd2e, v11
	v_mul_f32_e32 v11, 0.15915494, v12
	v_mul_f32_e32 v12, v166, v10
	v_mul_f32_e32 v13, 0.15915494, v12
	v_floor_f32_e32 v13, v13
	v_fmac_f32_e32 v12, 0xc0c90fdb, v13
	v_fmac_f32_e32 v12, 0x343bbd2e, v13
	v_mul_f32_e32 v12, 0.15915494, v12
	v_mul_f32_e32 v10, v167, v10
	v_cos_f32_e32 v18, v12
	v_sin_f32_e32 v20, v12
	v_mul_f32_e32 v12, 0.15915494, v10
	v_floor_f32_e32 v12, v12
	v_fmac_f32_e32 v10, 0xc0c90fdb, v12
	v_fmac_f32_e32 v10, 0x343bbd2e, v12
	v_mul_f32_e32 v10, 0.15915494, v10
	v_sin_f32_e32 v17, v11
	v_sin_f32_e32 v21, v10
	v_cos_f32_e32 v19, v10
	s_waitcnt lgkmcnt(0)
	s_mov_b64 s[12:13], s[48:49]
	v_cos_f32_e32 v15, v11
	s_lshl_b32 s10, s69, 2
	s_mov_b64 s[14:15], s[50:51]
	v_pk_mul_f32 v[10:11], v[16:17], v[2:3]
	v_pk_mul_f32 v[12:13], v[20:21], v[4:5]
	v_pk_mul_f32 v[22:23], v[16:17], v[6:7]
	v_pk_mul_f32 v[16:17], v[20:21], v[8:9]
	s_add_u32 s10, s14, s10
	v_pk_fma_f32 v[12:13], v[18:19], v[8:9], v[12:13] neg_lo:[0,0,1] neg_hi:[0,0,1]
	v_pk_fma_f32 v[16:17], v[18:19], v[4:5], v[16:17]
	s_addc_u32 s11, s15, 0
	v_lshlrev_b64 v[18:19], 7, v[76:77]
	v_lshl_add_u64 v[18:19], s[10:11], 0, v[18:19]
	v_lshlrev_b32_e32 v134, 2, v136
	v_pk_fma_f32 v[10:11], v[14:15], v[6:7], v[10:11] neg_lo:[0,0,1] neg_hi:[0,0,1]
	v_lshl_add_u64 v[18:19], v[18:19], 0, v[134:135]
	v_pk_fma_f32 v[14:15], v[14:15], v[2:3], v[22:23]
	global_store_dwordx4 v[18:19], v[10:13], off nt
	global_store_dwordx4 v[18:19], v[14:17], off offset:64 nt
	v_lshlrev_b64 v[18:19], 6, v[74:75]
	v_lshl_add_u64 v[18:19], v[138:139], 0, v[18:19]
	v_cvt_pk_bf16_f32 v10, v10, v11
	v_cvt_pk_bf16_f32 v11, v12, v13
	v_readlane_b32 s7, v244, 3
	v_readlane_b32 s6, v245, 57
	global_store_dwordx2 v[18:19], v[10:11], off
	v_cvt_pk_bf16_f32 v10, v14, v15
	v_cvt_pk_bf16_f32 v11, v16, v17
	global_store_dwordx2 v[18:19], v[10:11], off offset:32

.LBB0_567:
	s_andn2_b64 vcc, exec, s[12:13]
	s_cbranch_vccnz .LBB0_569
	v_readlane_b32 s0, v245, 37
	v_readlane_b32 s1, v245, 38
	s_load_dwordx16 s[36:51], s[0:1], 0x80
	s_lshl_b32 s10, s68, 2
	v_lshlrev_b64 v[10:11], 11, v[76:77]
	v_readlane_b32 s7, v244, 3
	v_readlane_b32 s6, v245, 57
	s_waitcnt lgkmcnt(0)
	s_mov_b64 s[12:13], s[48:49]
	s_mov_b64 s[14:15], s[50:51]
	s_add_u32 s10, s14, s10
	s_addc_u32 s11, s15, 0
	s_ashr_i32 s79, s78, 31
	v_lshl_add_u64 v[10:11], s[10:11], 0, v[10:11]
	v_lshl_add_u64 v[12:13], s[78:79], 0, v[144:145]
	v_lshl_add_u64 v[10:11], v[12:13], 2, v[10:11]
	global_store_dwordx4 v[10:11], v[6:9], off offset:512 nt
	global_store_dwordx4 v[10:11], v[2:5], off offset:576 nt
	v_lshlrev_b64 v[10:11], 10, v[74:75]
	v_lshl_add_u64 v[10:11], s[22:23], 0, v[10:11]
	v_lshl_add_u64 v[10:11], v[12:13], 1, v[10:11]
	v_cvt_pk_bf16_f32 v12, v6, v7
	v_cvt_pk_bf16_f32 v13, v8, v9
	global_store_dwordx2 v[10:11], v[12:13], off offset:256
	v_cvt_pk_bf16_f32 v12, v2, v3
	v_cvt_pk_bf16_f32 v13, v4, v5
	global_store_dwordx2 v[10:11], v[12:13], off offset:288

.LBB0_570:
	s_andn2_b64 vcc, exec, s[12:13]
	s_cbranch_vccnz .LBB0_572
	v_readlane_b32 s0, v245, 37
	v_readlane_b32 s1, v245, 38
	s_load_dwordx16 s[36:51], s[0:1], 0x80
	s_lshl_b32 s10, s61, 2
	v_lshlrev_b64 v[10:11], 11, v[76:77]
	v_readlane_b32 s7, v244, 3
	v_readlane_b32 s6, v245, 57
	s_waitcnt lgkmcnt(0)
	s_mov_b64 s[12:13], s[48:49]
	s_mov_b64 s[14:15], s[50:51]
	s_add_u32 s10, s14, s10
	s_addc_u32 s11, s15, 0
	s_ashr_i32 s79, s78, 31
	v_lshl_add_u64 v[10:11], s[10:11], 0, v[10:11]
	v_lshl_add_u64 v[12:13], s[78:79], 0, v[146:147]
	v_lshl_add_u64 v[10:11], v[12:13], 2, v[10:11]
	global_store_dwordx4 v[10:11], v[6:9], off offset:512 nt
	global_store_dwordx4 v[10:11], v[2:5], off offset:576 nt
	v_lshlrev_b64 v[10:11], 10, v[74:75]
	v_lshl_add_u64 v[10:11], s[28:29], 0, v[10:11]
	v_lshl_add_u64 v[10:11], v[12:13], 1, v[10:11]
	v_cvt_pk_bf16_f32 v12, v6, v7
	v_cvt_pk_bf16_f32 v13, v8, v9
	global_store_dwordx2 v[10:11], v[12:13], off offset:256
	v_cvt_pk_bf16_f32 v12, v2, v3
	v_cvt_pk_bf16_f32 v13, v4, v5
	global_store_dwordx2 v[10:11], v[12:13], off offset:288
